# rope epilogue: lane^16 exchange via one ds_bpermute per value instead of 2 v_mov + v_permlane16_swap + v_cndmask (instruction selection, VALU-bound epilogue)
# baseline (speedup 1.0000x reference)
; #define GAS __attribute__((address_space(1)))
; __device__ __forceinline__ unsigned pk2(float lo, float hi) { f32x2_t v = {lo, hi}; bf16x2_t b = __builtin_convertvector(v, bf16x2_t); return __builtin_bit_cast(unsigned, b); }
; __device__ __forceinline__ void swap16(float& a, float& b) { asm volatile("s_nop 1\n\tv_permlane16_swap_b32 %0, %1\n\ts_nop 1" : "+v"(a), "+v"(b)); }
; __device__ __forceinline__ float rstd_of(u64 q) { return __builtin_amdgcn_rsqf((float)q * (1.0f / (1024.0f * SS_SCALE)) + EPS); }
;     __device__ __forceinline__ void operator()(const AccT& acc, const Unit& u, int, int, int, int) const {
;     ...
;                 for (int m = 0; m < 4; ++m) {
;                     const int row = row0 + ai * HALF + m * 16; const float rs = rstd_of(sq[ai][m]);
;                     bf16_t* rp = QK + (size_t)row * NQK + col0;
;                     f32x4 c0 = tc0[m], c1 = tc1[m], s0 = ts0[m], s1 = ts1[m];
;                     if (fq == 0) { s0 = -s0; s1 = -s1; }
; #pragma unroll
;                     for (int bj = 0; bj < 2; ++bj) {
;                         f32x4 v0 = acc[ai][bj][m][0] * rs, v1 = acc[ai][bj][m][1] * rs;
;                         if (ropew) {
;                             f32x4 p0, p1;
; #pragma unroll
;                             for (int e = 0; e < 4; ++e) { float a0 = v0[e], b0 = v0[e], a1 = v1[e], b1 = v1[e]; swap16(a0, b0); swap16(a1, b1);
;                                 p0[e] = (fq & 1) ? a0 : b0; p1[e] = (fq & 1) ? a1 : b1; }
;                             v0 = v0 * c0 + p0 * s0; v1 = v1 * c1 + p1 * s1;
;                         }
;                         u32x4 w; w.x = pk2(v0[0], v0[1]); w.y = pk2(v0[2], v0[3]); w.z = pk2(v1[0], v1[1]); w.w = pk2(v1[2], v1[3]);
;                         *(GAS u32x4*)(rp + bj * HALF) = w;
;                     }
.LBB0_205:
	s_or_b64 exec, exec, s[2:3]
	s_waitcnt vmcnt(0)
	v_ffbh_u32_e32 v207, v223
	v_min_u32_e32 v207, 32, v207
	v_lshlrev_b64 v[226:227], v207, v[222:223]
	v_min_u32_e32 v225, 1, v226
	v_or_b32_e32 v225, v227, v225
	v_cvt_f32_u32_e32 v225, v225
	v_sub_u32_e32 v207, 32, v207
	v_and_b32_e32 v224, 16, v224
	v_xor_b32_e32 v226, 0x80000000, v189
	v_ldexp_f32 v207, v225, v207
	v_fmamk_f32 v207, v207, 0x30800000, v240
	v_rsq_f32_e32 v230, v207
	v_xor_b32_e32 v207, 0x80000000, v186
	v_xor_b32_e32 v231, 0x80000000, v190
	v_cmp_eq_u32_e64 s[6:7], 0, v0
	v_cmp_eq_u32_e64 s[2:3], 0, v224
	v_xor_b32_e32 v224, 0x80000000, v187
	v_xor_b32_e32 v225, 0x80000000, v188
	v_xor_b32_e32 v232, 0x80000000, v191
	v_xor_b32_e32 v233, 0x80000000, v192
	v_xor_b32_e32 v234, 0x80000000, v193
	v_cndmask_b32_e64 v229, v189, v226, s[6:7]
	v_cndmask_b32_e64 v226, v186, v207, s[6:7]
	v_cndmask_b32_e64 v186, v190, v231, s[6:7]
	v_cndmask_b32_e64 v190, 0, 1, s[34:35]
	v_cndmask_b32_e64 v228, v188, v225, s[6:7]
	v_cndmask_b32_e64 v227, v187, v224, s[6:7]
	v_cndmask_b32_e64 v189, v193, v234, s[6:7]
	v_cndmask_b32_e64 v188, v192, v233, s[6:7]
	v_cndmask_b32_e64 v187, v191, v232, s[6:7]
	v_pk_mul_f32 v[192:193], v[128:129], v[230:231] op_sel_hi:[1,0]
	v_pk_mul_f32 v[232:233], v[126:127], v[230:231] op_sel_hi:[1,0]
	v_pk_mul_f32 v[234:235], v[124:125], v[230:231] op_sel_hi:[1,0]
	v_cmp_ne_u32_e64 s[4:5], 1, v190
	s_andn2_b64 vcc, exec, s[34:35]
	v_pk_mul_f32 v[236:237], v[122:123], v[230:231] op_sel_hi:[1,0]
	s_cbranch_vccnz .LBB0_207
	v_xor_b32_e32 v207, 16, v238
	v_lshlrev_b32_e32 v207, 2, v207
	ds_bpermute_b32 v190, v207, v232
	ds_bpermute_b32 v224, v207, v236
	ds_bpermute_b32 v191, v207, v233
	ds_bpermute_b32 v225, v207, v237
	ds_bpermute_b32 v246, v207, v192
	ds_bpermute_b32 v248, v207, v234
	ds_bpermute_b32 v247, v207, v193
	ds_bpermute_b32 v249, v207, v235
	s_waitcnt lgkmcnt(0)
	v_pk_mul_f32 v[190:191], v[226:227], v[190:191]
	v_pk_mul_f32 v[246:247], v[228:229], v[246:247]
	v_pk_fma_f32 v[232:233], v[232:233], v[182:183], v[190:191]
	v_pk_mul_f32 v[190:191], v[188:189], v[248:249]
	v_pk_mul_f32 v[224:225], v[186:187], v[224:225]
	v_pk_fma_f32 v[192:193], v[192:193], v[184:185], v[246:247]
	v_pk_fma_f32 v[236:237], v[236:237], v[174:175], v[224:225]
	v_pk_fma_f32 v[234:235], v[234:235], v[176:177], v[190:191]
.LBB0_207:
	v_lshlrev_b32_e32 v190, 3, v0
	v_lshl_or_b32 v190, s21, 5, v190
	v_or_b32_e32 v224, s23, v190
	v_mov_b64_e32 v[190:191], s[10:11]
	v_mov_b32_e32 v231, v230
	v_ashrrev_i32_e32 v225, 31, v224
	v_mad_i64_i32 v[190:191], s[34:35], v206, s60, v[190:191]
	v_cvt_pk_bf16_f32 v247, v192, v193
	v_mov_b32_e32 v192, v230
	v_mov_b32_e32 v193, v230
	v_lshl_add_u64 v[190:191], v[224:225], 1, v[190:191]
	v_cvt_pk_bf16_f32 v246, v232, v233
	v_cvt_pk_bf16_f32 v248, v236, v237
	v_cvt_pk_bf16_f32 v249, v234, v235
	v_pk_mul_f32 v[232:233], v[120:121], v[192:193]
	v_pk_mul_f32 v[234:235], v[118:119], v[230:231]
	v_pk_mul_f32 v[192:193], v[116:117], v[192:193]
	s_and_b64 vcc, exec, s[4:5]
	v_pk_mul_f32 v[230:231], v[114:115], v[230:231]
	global_store_dwordx4 v[190:191], v[246:249], off
	s_cbranch_vccnz .LBB0_209
	v_xor_b32_e32 v207, 16, v238
	v_lshlrev_b32_e32 v207, 2, v207
	ds_bpermute_b32 v236, v207, v234
	ds_bpermute_b32 v246, v207, v230
	ds_bpermute_b32 v237, v207, v235
	ds_bpermute_b32 v247, v207, v231
	ds_bpermute_b32 v248, v207, v232
	ds_bpermute_b32 v250, v207, v192
	ds_bpermute_b32 v249, v207, v233
	ds_bpermute_b32 v251, v207, v193
	s_waitcnt lgkmcnt(0)
	v_pk_mul_f32 v[228:229], v[228:229], v[248:249]
	v_pk_mul_f32 v[226:227], v[226:227], v[236:237]
	v_pk_fma_f32 v[232:233], v[232:233], v[184:185], v[228:229]
	v_pk_fma_f32 v[234:235], v[234:235], v[182:183], v[226:227]
	v_pk_mul_f32 v[182:183], v[188:189], v[250:251]
	v_pk_mul_f32 v[184:185], v[186:187], v[246:247]
	v_pk_fma_f32 v[192:193], v[192:193], v[176:177], v[182:183]
	v_pk_fma_f32 v[230:231], v[230:231], v[174:175], v[184:185]
.LBB0_209:
	v_ffbh_u32_e32 v177, v221
	v_min_u32_e32 v184, 32, v177
	v_lshlrev_b64 v[182:183], v184, v[220:221]
	v_min_u32_e32 v177, 1, v182
	v_or_b32_e32 v177, v183, v177
	v_cvt_f32_u32_e32 v182, v177
	v_cvt_pk_bf16_f32 v174, v234, v235
	v_cvt_pk_bf16_f32 v175, v232, v233
	v_cvt_pk_bf16_f32 v176, v230, v231
	v_cvt_pk_bf16_f32 v177, v192, v193
	global_store_dwordx4 v[190:191], v[174:177], off offset:256
	v_xor_b32_e32 v183, 0x80000000, v178
	v_xor_b32_e32 v185, 0x80000000, v180
	v_sub_u32_e32 v174, 32, v184
	v_ldexp_f32 v174, v182, v174
	v_fmamk_f32 v174, v174, 0x30800000, v240
	v_rsq_f32_e32 v182, v174
	v_xor_b32_e32 v174, 0x80000000, v170
	v_xor_b32_e32 v175, 0x80000000, v171
	v_xor_b32_e32 v176, 0x80000000, v172
	v_xor_b32_e32 v177, 0x80000000, v173
	v_xor_b32_e32 v184, 0x80000000, v179
	v_xor_b32_e32 v186, 0x80000000, v181
	v_cndmask_b32_e64 v177, v173, v177, s[6:7]
	v_cndmask_b32_e64 v176, v172, v176, s[6:7]
	v_cndmask_b32_e64 v175, v171, v175, s[6:7]
	v_cndmask_b32_e64 v174, v170, v174, s[6:7]
	v_cndmask_b32_e64 v173, v181, v186, s[6:7]
	v_cndmask_b32_e64 v172, v180, v185, s[6:7]
	v_cndmask_b32_e64 v171, v179, v184, s[6:7]
	v_cndmask_b32_e64 v170, v178, v183, s[6:7]
	v_pk_mul_f32 v[180:181], v[112:113], v[182:183] op_sel_hi:[1,0]
	v_pk_mul_f32 v[184:185], v[110:111], v[182:183] op_sel_hi:[1,0]
	v_pk_mul_f32 v[186:187], v[108:109], v[182:183] op_sel_hi:[1,0]
	s_and_b64 vcc, exec, s[4:5]
	v_pk_mul_f32 v[188:189], v[106:107], v[182:183] op_sel_hi:[1,0]
	s_cbranch_vccnz .LBB0_211
	v_xor_b32_e32 v183, 16, v238
	v_lshlrev_b32_e32 v183, 2, v183
	ds_bpermute_b32 v178, v183, v184
	ds_bpermute_b32 v190, v183, v188
	ds_bpermute_b32 v179, v183, v185
	ds_bpermute_b32 v191, v183, v189
	ds_bpermute_b32 v192, v183, v180
	ds_bpermute_b32 v226, v183, v186
	ds_bpermute_b32 v193, v183, v181
	ds_bpermute_b32 v227, v183, v187
	s_waitcnt lgkmcnt(0)
	v_pk_mul_f32 v[178:179], v[174:175], v[178:179]
	v_pk_mul_f32 v[192:193], v[176:177], v[192:193]
	v_pk_fma_f32 v[184:185], v[184:185], v[158:159], v[178:179]
	v_pk_mul_f32 v[178:179], v[172:173], v[226:227]
	v_pk_mul_f32 v[190:191], v[170:171], v[190:191]
	v_pk_fma_f32 v[180:181], v[180:181], v[160:161], v[192:193]
	v_pk_fma_f32 v[188:189], v[188:189], v[154:155], v[190:191]
	v_pk_fma_f32 v[186:187], v[186:187], v[156:157], v[178:179]
; #define GAS __attribute__((address_space(1)))
; __device__ __forceinline__ unsigned pk2(float lo, float hi) { f32x2_t v = {lo, hi}; bf16x2_t b = __builtin_convertvector(v, bf16x2_t); return __builtin_bit_cast(unsigned, b); }
; __device__ __forceinline__ void swap16(float& a, float& b) { asm volatile("s_nop 1\n\tv_permlane16_swap_b32 %0, %1\n\ts_nop 1" : "+v"(a), "+v"(b)); }
; __device__ __forceinline__ float rstd_of(u64 q) { return __builtin_amdgcn_rsqf((float)q * (1.0f / (1024.0f * SS_SCALE)) + EPS); }
;     __device__ __forceinline__ void operator()(const AccT& acc, const Unit& u, int, int, int, int) const {
;     ...
;                 for (int m = 0; m < 4; ++m) {
;                     const int row = row0 + ai * HALF + m * 16; const float rs = rstd_of(sq[ai][m]);
;                     bf16_t* rp = QK + (size_t)row * NQK + col0;
;                     f32x4 c0 = tc0[m], c1 = tc1[m], s0 = ts0[m], s1 = ts1[m];
;                     if (fq == 0) { s0 = -s0; s1 = -s1; }
; #pragma unroll
;                     for (int bj = 0; bj < 2; ++bj) {
;                         f32x4 v0 = acc[ai][bj][m][0] * rs, v1 = acc[ai][bj][m][1] * rs;
;                         if (ropew) {
;                             f32x4 p0, p1;
; #pragma unroll
;                             for (int e = 0; e < 4; ++e) { float a0 = v0[e], b0 = v0[e], a1 = v1[e], b1 = v1[e]; swap16(a0, b0); swap16(a1, b1);
;                                 p0[e] = (fq & 1) ? a0 : b0; p1[e] = (fq & 1) ? a1 : b1; }
;                             v0 = v0 * c0 + p0 * s0; v1 = v1 * c1 + p1 * s1;
;                         }
;                         u32x4 w; w.x = pk2(v0[0], v0[1]); w.y = pk2(v0[2], v0[3]); w.z = pk2(v1[0], v1[1]); w.w = pk2(v1[2], v1[3]);
;                         *(GAS u32x4*)(rp + bj * HALF) = w;
;                     }
.LBB0_211:
	v_or_b32_e32 v190, 16, v206
	v_mov_b64_e32 v[178:179], s[10:11]
	v_mov_b32_e32 v183, v182
	v_mad_i64_i32 v[178:179], s[34:35], v190, s60, v[178:179]
	v_cvt_pk_bf16_f32 v191, v180, v181
	v_mov_b32_e32 v180, v182
	v_mov_b32_e32 v181, v182
	v_lshl_add_u64 v[178:179], v[224:225], 1, v[178:179]
	v_cvt_pk_bf16_f32 v190, v184, v185
	v_cvt_pk_bf16_f32 v192, v188, v189
	v_cvt_pk_bf16_f32 v193, v186, v187
	v_pk_mul_f32 v[184:185], v[104:105], v[180:181]
	v_pk_mul_f32 v[186:187], v[102:103], v[182:183]
	v_pk_mul_f32 v[180:181], v[100:101], v[180:181]
	s_and_b64 vcc, exec, s[4:5]
	v_pk_mul_f32 v[182:183], v[98:99], v[182:183]
	global_store_dwordx4 v[178:179], v[190:193], off
	s_cbranch_vccnz .LBB0_213
	v_xor_b32_e32 v207, 16, v238
	v_lshlrev_b32_e32 v207, 2, v207
	ds_bpermute_b32 v188, v207, v186
	ds_bpermute_b32 v190, v207, v182
	ds_bpermute_b32 v189, v207, v187
	ds_bpermute_b32 v191, v207, v183
	ds_bpermute_b32 v192, v207, v184
	ds_bpermute_b32 v226, v207, v180
	ds_bpermute_b32 v193, v207, v185
	ds_bpermute_b32 v227, v207, v181
	s_waitcnt lgkmcnt(0)
	v_pk_mul_f32 v[176:177], v[176:177], v[192:193]
	v_pk_mul_f32 v[174:175], v[174:175], v[188:189]
	v_pk_fma_f32 v[184:185], v[184:185], v[160:161], v[176:177]
	v_pk_fma_f32 v[186:187], v[186:187], v[158:159], v[174:175]
	v_pk_mul_f32 v[158:159], v[172:173], v[226:227]
	v_pk_mul_f32 v[160:161], v[170:171], v[190:191]
	v_pk_fma_f32 v[180:181], v[180:181], v[156:157], v[158:159]
	v_pk_fma_f32 v[182:183], v[182:183], v[154:155], v[160:161]
.LBB0_213:
	v_ffbh_u32_e32 v157, v219
	v_min_u32_e32 v160, 32, v157
	v_lshlrev_b64 v[158:159], v160, v[218:219]
	v_min_u32_e32 v157, 1, v158
	v_or_b32_e32 v157, v159, v157
	v_cvt_f32_u32_e32 v158, v157
	v_cvt_pk_bf16_f32 v154, v186, v187
	v_cvt_pk_bf16_f32 v155, v184, v185
	v_cvt_pk_bf16_f32 v156, v182, v183
	v_cvt_pk_bf16_f32 v157, v180, v181
	global_store_dwordx4 v[178:179], v[154:157], off offset:256
	v_xor_b32_e32 v171, 0x80000000, v166
	v_xor_b32_e32 v172, 0x80000000, v167
	v_sub_u32_e32 v154, 32, v160
	v_ldexp_f32 v154, v158, v154
	v_fmamk_f32 v154, v154, 0x30800000, v240
	v_rsq_f32_e32 v170, v154
	v_xor_b32_e32 v154, 0x80000000, v162
	v_xor_b32_e32 v155, 0x80000000, v163
	v_xor_b32_e32 v156, 0x80000000, v164
	v_xor_b32_e32 v157, 0x80000000, v165
	v_xor_b32_e32 v173, 0x80000000, v168
	v_xor_b32_e32 v174, 0x80000000, v169
	v_cndmask_b32_e64 v161, v165, v157, s[6:7]
	v_cndmask_b32_e64 v160, v164, v156, s[6:7]
	v_cndmask_b32_e64 v159, v163, v155, s[6:7]
	v_cndmask_b32_e64 v158, v162, v154, s[6:7]
	v_cndmask_b32_e64 v157, v169, v174, s[6:7]
	v_cndmask_b32_e64 v156, v168, v173, s[6:7]
	v_cndmask_b32_e64 v155, v167, v172, s[6:7]
	v_cndmask_b32_e64 v154, v166, v171, s[6:7]
	v_pk_mul_f32 v[164:165], v[96:97], v[170:171] op_sel_hi:[1,0]
	v_pk_mul_f32 v[166:167], v[94:95], v[170:171] op_sel_hi:[1,0]
	v_pk_mul_f32 v[168:169], v[92:93], v[170:171] op_sel_hi:[1,0]
	s_and_b64 vcc, exec, s[4:5]
	v_pk_mul_f32 v[172:173], v[90:91], v[170:171] op_sel_hi:[1,0]
	s_cbranch_vccnz .LBB0_215
	v_xor_b32_e32 v171, 16, v238
	v_lshlrev_b32_e32 v171, 2, v171
	ds_bpermute_b32 v162, v171, v166
	ds_bpermute_b32 v174, v171, v172
	ds_bpermute_b32 v163, v171, v167
	ds_bpermute_b32 v175, v171, v173
	ds_bpermute_b32 v176, v171, v164
	ds_bpermute_b32 v178, v171, v168
	ds_bpermute_b32 v177, v171, v165
	ds_bpermute_b32 v179, v171, v169
	s_waitcnt lgkmcnt(0)
	v_pk_mul_f32 v[162:163], v[158:159], v[162:163]
	v_pk_mul_f32 v[176:177], v[160:161], v[176:177]
	v_pk_fma_f32 v[166:167], v[166:167], v[150:151], v[162:163]
	v_pk_mul_f32 v[162:163], v[156:157], v[178:179]
	v_pk_mul_f32 v[174:175], v[154:155], v[174:175]
	v_pk_fma_f32 v[164:165], v[164:165], v[152:153], v[176:177]
	v_pk_fma_f32 v[172:173], v[172:173], v[142:143], v[174:175]
	v_pk_fma_f32 v[168:169], v[168:169], v[144:145], v[162:163]
; #define GAS __attribute__((address_space(1)))
; __device__ __forceinline__ unsigned pk2(float lo, float hi) { f32x2_t v = {lo, hi}; bf16x2_t b = __builtin_convertvector(v, bf16x2_t); return __builtin_bit_cast(unsigned, b); }
; __device__ __forceinline__ void swap16(float& a, float& b) { asm volatile("s_nop 1\n\tv_permlane16_swap_b32 %0, %1\n\ts_nop 1" : "+v"(a), "+v"(b)); }
; __device__ __forceinline__ float rstd_of(u64 q) { return __builtin_amdgcn_rsqf((float)q * (1.0f / (1024.0f * SS_SCALE)) + EPS); }
;     __device__ __forceinline__ void operator()(const AccT& acc, const Unit& u, int, int, int, int) const {
;     ...
;                 for (int m = 0; m < 4; ++m) {
;                     const int row = row0 + ai * HALF + m * 16; const float rs = rstd_of(sq[ai][m]);
;                     bf16_t* rp = QK + (size_t)row * NQK + col0;
;                     f32x4 c0 = tc0[m], c1 = tc1[m], s0 = ts0[m], s1 = ts1[m];
;                     if (fq == 0) { s0 = -s0; s1 = -s1; }
; #pragma unroll
;                     for (int bj = 0; bj < 2; ++bj) {
;                         f32x4 v0 = acc[ai][bj][m][0] * rs, v1 = acc[ai][bj][m][1] * rs;
;                         if (ropew) {
;                             f32x4 p0, p1;
; #pragma unroll
;                             for (int e = 0; e < 4; ++e) { float a0 = v0[e], b0 = v0[e], a1 = v1[e], b1 = v1[e]; swap16(a0, b0); swap16(a1, b1);
;                                 p0[e] = (fq & 1) ? a0 : b0; p1[e] = (fq & 1) ? a1 : b1; }
;                             v0 = v0 * c0 + p0 * s0; v1 = v1 * c1 + p1 * s1;
;                         }
;                         u32x4 w; w.x = pk2(v0[0], v0[1]); w.y = pk2(v0[2], v0[3]); w.z = pk2(v1[0], v1[1]); w.w = pk2(v1[2], v1[3]);
;                         *(GAS u32x4*)(rp + bj * HALF) = w;
;                     }
.LBB0_215:
	v_or_b32_e32 v174, 32, v206
	v_mov_b64_e32 v[162:163], s[10:11]
	v_mov_b32_e32 v171, v170
	v_mad_i64_i32 v[162:163], s[34:35], v174, s60, v[162:163]
	v_cvt_pk_bf16_f32 v175, v164, v165
	v_mov_b32_e32 v164, v170
	v_mov_b32_e32 v165, v170
	v_lshl_add_u64 v[162:163], v[224:225], 1, v[162:163]
	v_cvt_pk_bf16_f32 v174, v166, v167
	v_cvt_pk_bf16_f32 v176, v172, v173
	v_cvt_pk_bf16_f32 v177, v168, v169
	v_pk_mul_f32 v[166:167], v[88:89], v[164:165]
	v_pk_mul_f32 v[168:169], v[86:87], v[170:171]
	v_pk_mul_f32 v[164:165], v[84:85], v[164:165]
	s_and_b64 vcc, exec, s[4:5]
	v_pk_mul_f32 v[170:171], v[82:83], v[170:171]
	global_store_dwordx4 v[162:163], v[174:177], off
	s_cbranch_vccnz .LBB0_217
	v_xor_b32_e32 v180, 16, v238
	v_lshlrev_b32_e32 v180, 2, v180
	ds_bpermute_b32 v172, v180, v168
	ds_bpermute_b32 v174, v180, v170
	ds_bpermute_b32 v173, v180, v169
	ds_bpermute_b32 v175, v180, v171
	ds_bpermute_b32 v176, v180, v166
	ds_bpermute_b32 v178, v180, v164
	ds_bpermute_b32 v177, v180, v167
	ds_bpermute_b32 v179, v180, v165
	s_waitcnt lgkmcnt(0)
	v_pk_mul_f32 v[160:161], v[160:161], v[176:177]
	v_pk_mul_f32 v[158:159], v[158:159], v[172:173]
	v_pk_fma_f32 v[166:167], v[166:167], v[152:153], v[160:161]
	v_pk_fma_f32 v[168:169], v[168:169], v[150:151], v[158:159]
	v_pk_mul_f32 v[150:151], v[156:157], v[178:179]
	v_pk_mul_f32 v[152:153], v[154:155], v[174:175]
	v_pk_fma_f32 v[164:165], v[164:165], v[144:145], v[150:151]
	v_pk_fma_f32 v[170:171], v[170:171], v[142:143], v[152:153]
.LBB0_217:
	v_ffbh_u32_e32 v145, v217
	v_min_u32_e32 v152, 32, v145
	v_lshlrev_b64 v[150:151], v152, v[216:217]
	v_min_u32_e32 v145, 1, v150
	v_or_b32_e32 v145, v151, v145
	v_cvt_f32_u32_e32 v150, v145
	v_cvt_pk_bf16_f32 v142, v168, v169
	v_cvt_pk_bf16_f32 v143, v166, v167
	v_cvt_pk_bf16_f32 v144, v170, v171
	v_cvt_pk_bf16_f32 v145, v164, v165
	global_store_dwordx4 v[162:163], v[142:145], off offset:256
	v_xor_b32_e32 v151, 0x80000000, v146
	v_xor_b32_e32 v153, 0x80000000, v148
	v_sub_u32_e32 v142, 32, v152
	v_ldexp_f32 v142, v150, v142
	v_fmamk_f32 v142, v142, 0x30800000, v240
	v_rsq_f32_e32 v150, v142
	v_xor_b32_e32 v142, 0x80000000, v138
	v_xor_b32_e32 v143, 0x80000000, v139
	v_xor_b32_e32 v144, 0x80000000, v140
	v_xor_b32_e32 v145, 0x80000000, v141
	v_xor_b32_e32 v152, 0x80000000, v147
	v_xor_b32_e32 v154, 0x80000000, v149
	v_cndmask_b32_e64 v145, v141, v145, s[6:7]
	v_cndmask_b32_e64 v144, v140, v144, s[6:7]
	v_cndmask_b32_e64 v143, v139, v143, s[6:7]
	v_cndmask_b32_e64 v142, v138, v142, s[6:7]
	v_cndmask_b32_e64 v141, v149, v154, s[6:7]
	v_cndmask_b32_e64 v140, v148, v153, s[6:7]
	v_cndmask_b32_e64 v139, v147, v152, s[6:7]
	v_cndmask_b32_e64 v138, v146, v151, s[6:7]
	v_pk_mul_f32 v[148:149], v[80:81], v[150:151] op_sel_hi:[1,0]
	v_pk_mul_f32 v[152:153], v[78:79], v[150:151] op_sel_hi:[1,0]
	v_pk_mul_f32 v[154:155], v[76:77], v[150:151] op_sel_hi:[1,0]
	s_and_b64 vcc, exec, s[4:5]
	v_pk_mul_f32 v[156:157], v[74:75], v[150:151] op_sel_hi:[1,0]
	s_cbranch_vccnz .LBB0_219
	v_xor_b32_e32 v151, 16, v238
	v_lshlrev_b32_e32 v151, 2, v151
	ds_bpermute_b32 v146, v151, v152
	ds_bpermute_b32 v158, v151, v156
	ds_bpermute_b32 v147, v151, v153
	ds_bpermute_b32 v159, v151, v157
	ds_bpermute_b32 v160, v151, v148
	ds_bpermute_b32 v162, v151, v154
	ds_bpermute_b32 v161, v151, v149
	ds_bpermute_b32 v163, v151, v155
	s_waitcnt lgkmcnt(0)
	v_pk_mul_f32 v[146:147], v[142:143], v[146:147]
	v_pk_mul_f32 v[160:161], v[144:145], v[160:161]
	v_pk_fma_f32 v[152:153], v[152:153], v[134:135], v[146:147]
	v_pk_mul_f32 v[146:147], v[140:141], v[162:163]
	v_pk_mul_f32 v[158:159], v[138:139], v[158:159]
	v_pk_fma_f32 v[148:149], v[148:149], v[136:137], v[160:161]
	v_pk_fma_f32 v[156:157], v[156:157], v[130:131], v[158:159]
	v_pk_fma_f32 v[154:155], v[154:155], v[132:133], v[146:147]
.LBB0_219:
	v_or_b32_e32 v158, 48, v206
	v_mov_b64_e32 v[146:147], s[10:11]
	v_mov_b32_e32 v151, v150
	v_mad_i64_i32 v[146:147], s[34:35], v158, s60, v[146:147]
	v_cvt_pk_bf16_f32 v161, v154, v155
	v_mov_b32_e32 v154, v150
	v_mov_b32_e32 v155, v150
	v_lshl_add_u64 v[146:147], v[224:225], 1, v[146:147]
	v_cvt_pk_bf16_f32 v158, v152, v153
	v_cvt_pk_bf16_f32 v159, v148, v149
	v_cvt_pk_bf16_f32 v160, v156, v157
	v_pk_mul_f32 v[148:149], v[72:73], v[154:155]
	v_pk_mul_f32 v[152:153], v[70:71], v[150:151]
	v_pk_mul_f32 v[154:155], v[68:69], v[154:155]
	s_and_b64 vcc, exec, s[4:5]
	v_pk_mul_f32 v[150:151], v[66:67], v[150:151]
	global_store_dwordx4 v[146:147], v[158:161], off
	s_cbranch_vccnz .LBB0_221
	v_xor_b32_e32 v164, 16, v238
	v_lshlrev_b32_e32 v164, 2, v164
	ds_bpermute_b32 v156, v164, v152
	ds_bpermute_b32 v158, v164, v150
	ds_bpermute_b32 v157, v164, v153
	ds_bpermute_b32 v159, v164, v151
	ds_bpermute_b32 v160, v164, v148
	ds_bpermute_b32 v162, v164, v154
	ds_bpermute_b32 v161, v164, v149
	ds_bpermute_b32 v163, v164, v155
	s_waitcnt lgkmcnt(0)
	v_pk_mul_f32 v[144:145], v[144:145], v[160:161]
	v_pk_mul_f32 v[142:143], v[142:143], v[156:157]
	v_pk_fma_f32 v[148:149], v[148:149], v[136:137], v[144:145]
	v_pk_fma_f32 v[152:153], v[152:153], v[134:135], v[142:143]
	v_pk_mul_f32 v[134:135], v[140:141], v[162:163]
	v_pk_mul_f32 v[136:137], v[138:139], v[158:159]
	v_pk_fma_f32 v[154:155], v[154:155], v[132:133], v[134:135]
	v_pk_fma_f32 v[150:151], v[150:151], v[130:131], v[136:137]

; #define GAS __attribute__((address_space(1)))
; __device__ __forceinline__ unsigned pk2(float lo, float hi) { f32x2_t v = {lo, hi}; bf16x2_t b = __builtin_convertvector(v, bf16x2_t); return __builtin_bit_cast(unsigned, b); }
; __device__ __forceinline__ void swap16(float& a, float& b) { asm volatile("s_nop 1\n\tv_permlane16_swap_b32 %0, %1\n\ts_nop 1" : "+v"(a), "+v"(b)); }
; __device__ __forceinline__ float rstd_of(u64 q) { return __builtin_amdgcn_rsqf((float)q * (1.0f / (1024.0f * SS_SCALE)) + EPS); }
;     __device__ __forceinline__ void operator()(const AccT& acc, const Unit& u, int, int, int, int) const {
;     ...
;                 for (int m = 0; m < 4; ++m) {
;                     const int row = row0 + ai * HALF + m * 16; const float rs = rstd_of(sq[ai][m]);
;                     bf16_t* rp = QK + (size_t)row * NQK + col0;
;                     f32x4 c0 = tc0[m], c1 = tc1[m], s0 = ts0[m], s1 = ts1[m];
;                     if (fq == 0) { s0 = -s0; s1 = -s1; }
; #pragma unroll
;                     for (int bj = 0; bj < 2; ++bj) {
;                         f32x4 v0 = acc[ai][bj][m][0] * rs, v1 = acc[ai][bj][m][1] * rs;
;                         if (ropew) {
;                             f32x4 p0, p1;
; #pragma unroll
;                             for (int e = 0; e < 4; ++e) { float a0 = v0[e], b0 = v0[e], a1 = v1[e], b1 = v1[e]; swap16(a0, b0); swap16(a1, b1);
;                                 p0[e] = (fq & 1) ? a0 : b0; p1[e] = (fq & 1) ? a1 : b1; }
;                             v0 = v0 * c0 + p0 * s0; v1 = v1 * c1 + p1 * s1;
;                         }
;                         u32x4 w; w.x = pk2(v0[0], v0[1]); w.y = pk2(v0[2], v0[3]); w.z = pk2(v1[0], v1[1]); w.w = pk2(v1[2], v1[3]);
;                         *(GAS u32x4*)(rp + bj * HALF) = w;
;                     }
.LBB0_229:
	s_or_b64 exec, exec, s[34:35]
	v_ffbh_u32_e32 v226, v215
	v_min_u32_e32 v228, 32, v226
	v_lshlrev_b64 v[226:227], v228, v[214:215]
	v_min_u32_e32 v226, 1, v226
	v_or_b32_e32 v226, v227, v226
	v_cvt_f32_u32_e32 v226, v226
	v_sub_u32_e32 v228, 32, v228
	s_waitcnt vmcnt(3)
	v_xor_b32_e32 v231, 0x80000000, v186
	v_xor_b32_e32 v227, 0x80000000, v187
	v_ldexp_f32 v226, v226, v228
	v_fmamk_f32 v226, v226, 0x30800000, v240
	v_rsq_f32_e32 v230, v226
	v_xor_b32_e32 v226, 0x80000000, v188
	v_xor_b32_e32 v228, 0x80000000, v189
	s_waitcnt vmcnt(2)
	v_xor_b32_e32 v232, 0x80000000, v190
	v_xor_b32_e32 v233, 0x80000000, v191
	v_xor_b32_e32 v234, 0x80000000, v192
	v_xor_b32_e32 v235, 0x80000000, v193
	v_cndmask_b32_e64 v229, v189, v228, s[6:7]
	v_cndmask_b32_e64 v228, v188, v226, s[6:7]
	v_cndmask_b32_e64 v227, v187, v227, s[6:7]
	v_cndmask_b32_e64 v226, v186, v231, s[6:7]
	v_cndmask_b32_e64 v189, v193, v235, s[6:7]
	v_cndmask_b32_e64 v188, v192, v234, s[6:7]
	v_cndmask_b32_e64 v187, v191, v233, s[6:7]
	v_cndmask_b32_e64 v186, v190, v232, s[6:7]
	v_pk_mul_f32 v[192:193], v[64:65], v[230:231] op_sel_hi:[1,0]
	v_pk_mul_f32 v[232:233], v[62:63], v[230:231] op_sel_hi:[1,0]
	v_pk_mul_f32 v[234:235], v[60:61], v[230:231] op_sel_hi:[1,0]
	s_and_b64 vcc, exec, s[4:5]
	v_pk_mul_f32 v[236:237], v[58:59], v[230:231] op_sel_hi:[1,0]
	s_cbranch_vccnz .LBB0_231
	v_xor_b32_e32 v231, 16, v238
	v_lshlrev_b32_e32 v231, 2, v231
	ds_bpermute_b32 v190, v231, v232
	ds_bpermute_b32 v246, v231, v236
	ds_bpermute_b32 v191, v231, v233
	ds_bpermute_b32 v247, v231, v237
	ds_bpermute_b32 v248, v231, v192
	ds_bpermute_b32 v250, v231, v234
	ds_bpermute_b32 v249, v231, v193
	ds_bpermute_b32 v251, v231, v235
	s_waitcnt lgkmcnt(0)
	v_pk_mul_f32 v[190:191], v[226:227], v[190:191]
	v_pk_mul_f32 v[248:249], v[228:229], v[248:249]
	s_waitcnt vmcnt(0)
	v_pk_fma_f32 v[232:233], v[232:233], v[182:183], v[190:191]
	v_pk_mul_f32 v[190:191], v[188:189], v[250:251]
	v_pk_mul_f32 v[246:247], v[186:187], v[246:247]
	v_pk_fma_f32 v[192:193], v[192:193], v[184:185], v[248:249]
	v_pk_fma_f32 v[236:237], v[236:237], v[174:175], v[246:247]
	v_pk_fma_f32 v[234:235], v[234:235], v[176:177], v[190:191]
.LBB0_231:
	v_mov_b64_e32 v[190:191], s[10:11]
	v_mov_b32_e32 v231, v230
	v_mad_i64_i32 v[190:191], s[30:31], v207, s60, v[190:191]
	v_cvt_pk_bf16_f32 v247, v192, v193
	v_mov_b32_e32 v192, v230
	v_mov_b32_e32 v193, v230
	v_lshl_add_u64 v[190:191], v[224:225], 1, v[190:191]
	v_cvt_pk_bf16_f32 v246, v232, v233
	v_cvt_pk_bf16_f32 v248, v236, v237
	v_cvt_pk_bf16_f32 v249, v234, v235
	v_pk_mul_f32 v[232:233], v[56:57], v[192:193]
	v_pk_mul_f32 v[234:235], v[54:55], v[230:231]
	v_pk_mul_f32 v[192:193], v[52:53], v[192:193]
	s_and_b64 vcc, exec, s[4:5]
	v_pk_mul_f32 v[230:231], v[50:51], v[230:231]
	global_store_dwordx4 v[190:191], v[246:249], off
	s_cbranch_vccnz .LBB0_233
	v_xor_b32_e32 v207, 16, v238
	v_lshlrev_b32_e32 v207, 2, v207
	ds_bpermute_b32 v236, v207, v234
	ds_bpermute_b32 v246, v207, v230
	ds_bpermute_b32 v237, v207, v235
	ds_bpermute_b32 v247, v207, v231
	ds_bpermute_b32 v248, v207, v232
	ds_bpermute_b32 v250, v207, v192
	ds_bpermute_b32 v249, v207, v233
	ds_bpermute_b32 v251, v207, v193
	s_waitcnt lgkmcnt(0)
	v_pk_mul_f32 v[228:229], v[228:229], v[248:249]
	v_pk_mul_f32 v[226:227], v[226:227], v[236:237]
	s_waitcnt vmcnt(1)
	v_pk_fma_f32 v[232:233], v[232:233], v[184:185], v[228:229]
	v_pk_fma_f32 v[234:235], v[234:235], v[182:183], v[226:227]
	v_pk_mul_f32 v[182:183], v[188:189], v[250:251]
	v_pk_mul_f32 v[184:185], v[186:187], v[246:247]
	v_pk_fma_f32 v[192:193], v[192:193], v[176:177], v[182:183]
	v_pk_fma_f32 v[230:231], v[230:231], v[174:175], v[184:185]
.LBB0_233:
	s_waitcnt vmcnt(2)
	v_ffbh_u32_e32 v177, v213
	s_waitcnt vmcnt(1)
	v_min_u32_e32 v184, 32, v177
	v_lshlrev_b64 v[182:183], v184, v[212:213]
	v_min_u32_e32 v177, 1, v182
	v_or_b32_e32 v177, v183, v177
	v_cvt_f32_u32_e32 v182, v177
	v_cvt_pk_bf16_f32 v174, v234, v235
	v_cvt_pk_bf16_f32 v175, v232, v233
	v_cvt_pk_bf16_f32 v176, v230, v231
	v_cvt_pk_bf16_f32 v177, v192, v193
	global_store_dwordx4 v[190:191], v[174:177], off offset:256
	v_xor_b32_e32 v183, 0x80000000, v178
	v_xor_b32_e32 v185, 0x80000000, v180
	v_sub_u32_e32 v174, 32, v184
	v_ldexp_f32 v174, v182, v174
	v_fmamk_f32 v174, v174, 0x30800000, v240
	v_rsq_f32_e32 v182, v174
	v_xor_b32_e32 v174, 0x80000000, v170
	v_xor_b32_e32 v175, 0x80000000, v171
	v_xor_b32_e32 v176, 0x80000000, v172
	v_xor_b32_e32 v177, 0x80000000, v173
	v_xor_b32_e32 v184, 0x80000000, v179
	v_xor_b32_e32 v186, 0x80000000, v181
	v_cndmask_b32_e64 v177, v173, v177, s[6:7]
	v_cndmask_b32_e64 v176, v172, v176, s[6:7]
	v_cndmask_b32_e64 v175, v171, v175, s[6:7]
	v_cndmask_b32_e64 v174, v170, v174, s[6:7]
	v_cndmask_b32_e64 v173, v181, v186, s[6:7]
	v_cndmask_b32_e64 v172, v180, v185, s[6:7]
	v_cndmask_b32_e64 v171, v179, v184, s[6:7]
	v_cndmask_b32_e64 v170, v178, v183, s[6:7]
	v_pk_mul_f32 v[180:181], v[48:49], v[182:183] op_sel_hi:[1,0]
	v_pk_mul_f32 v[184:185], v[46:47], v[182:183] op_sel_hi:[1,0]
	v_pk_mul_f32 v[186:187], v[44:45], v[182:183] op_sel_hi:[1,0]
	s_and_b64 vcc, exec, s[4:5]
	v_pk_mul_f32 v[188:189], v[42:43], v[182:183] op_sel_hi:[1,0]
	s_cbranch_vccnz .LBB0_235
	v_xor_b32_e32 v183, 16, v238
	v_lshlrev_b32_e32 v183, 2, v183
	ds_bpermute_b32 v178, v183, v184
	ds_bpermute_b32 v190, v183, v188
	ds_bpermute_b32 v179, v183, v185
	ds_bpermute_b32 v191, v183, v189
	ds_bpermute_b32 v192, v183, v180
	ds_bpermute_b32 v226, v183, v186
	ds_bpermute_b32 v193, v183, v181
	ds_bpermute_b32 v227, v183, v187
	s_waitcnt lgkmcnt(0)
	v_pk_mul_f32 v[178:179], v[174:175], v[178:179]
	v_pk_mul_f32 v[192:193], v[176:177], v[192:193]
	v_pk_fma_f32 v[184:185], v[184:185], v[166:167], v[178:179]
	v_pk_mul_f32 v[178:179], v[172:173], v[226:227]
	v_pk_mul_f32 v[190:191], v[170:171], v[190:191]
	v_pk_fma_f32 v[180:181], v[180:181], v[168:169], v[192:193]
	v_pk_fma_f32 v[188:189], v[188:189], v[154:155], v[190:191]
	v_pk_fma_f32 v[186:187], v[186:187], v[156:157], v[178:179]
; #define GAS __attribute__((address_space(1)))
; __device__ __forceinline__ unsigned pk2(float lo, float hi) { f32x2_t v = {lo, hi}; bf16x2_t b = __builtin_convertvector(v, bf16x2_t); return __builtin_bit_cast(unsigned, b); }
; __device__ __forceinline__ void swap16(float& a, float& b) { asm volatile("s_nop 1\n\tv_permlane16_swap_b32 %0, %1\n\ts_nop 1" : "+v"(a), "+v"(b)); }
; __device__ __forceinline__ float rstd_of(u64 q) { return __builtin_amdgcn_rsqf((float)q * (1.0f / (1024.0f * SS_SCALE)) + EPS); }
;     __device__ __forceinline__ void operator()(const AccT& acc, const Unit& u, int, int, int, int) const {
;     ...
;                 for (int m = 0; m < 4; ++m) {
;                     const int row = row0 + ai * HALF + m * 16; const float rs = rstd_of(sq[ai][m]);
;                     bf16_t* rp = QK + (size_t)row * NQK + col0;
;                     f32x4 c0 = tc0[m], c1 = tc1[m], s0 = ts0[m], s1 = ts1[m];
;                     if (fq == 0) { s0 = -s0; s1 = -s1; }
; #pragma unroll
;                     for (int bj = 0; bj < 2; ++bj) {
;                         f32x4 v0 = acc[ai][bj][m][0] * rs, v1 = acc[ai][bj][m][1] * rs;
;                         if (ropew) {
;                             f32x4 p0, p1;
; #pragma unroll
;                             for (int e = 0; e < 4; ++e) { float a0 = v0[e], b0 = v0[e], a1 = v1[e], b1 = v1[e]; swap16(a0, b0); swap16(a1, b1);
;                                 p0[e] = (fq & 1) ? a0 : b0; p1[e] = (fq & 1) ? a1 : b1; }
;                             v0 = v0 * c0 + p0 * s0; v1 = v1 * c1 + p1 * s1;
;                         }
;                         u32x4 w; w.x = pk2(v0[0], v0[1]); w.y = pk2(v0[2], v0[3]); w.z = pk2(v1[0], v1[1]); w.w = pk2(v1[2], v1[3]);
;                         *(GAS u32x4*)(rp + bj * HALF) = w;
;                     }
.LBB0_235:
	v_add_u32_e32 v190, 0x90, v206
	v_mov_b64_e32 v[178:179], s[10:11]
	v_mov_b32_e32 v183, v182
	v_mad_i64_i32 v[178:179], s[30:31], v190, s60, v[178:179]
	v_cvt_pk_bf16_f32 v191, v180, v181
	v_mov_b32_e32 v180, v182
	v_mov_b32_e32 v181, v182
	v_lshl_add_u64 v[178:179], v[224:225], 1, v[178:179]
	v_cvt_pk_bf16_f32 v190, v184, v185
	v_cvt_pk_bf16_f32 v192, v188, v189
	v_cvt_pk_bf16_f32 v193, v186, v187
	v_pk_mul_f32 v[184:185], v[40:41], v[180:181]
	v_pk_mul_f32 v[186:187], v[38:39], v[182:183]
	v_pk_mul_f32 v[180:181], v[36:37], v[180:181]
	s_and_b64 vcc, exec, s[4:5]
	v_pk_mul_f32 v[182:183], v[34:35], v[182:183]
	global_store_dwordx4 v[178:179], v[190:193], off
	s_cbranch_vccnz .LBB0_237
	v_xor_b32_e32 v207, 16, v238
	v_lshlrev_b32_e32 v207, 2, v207
	ds_bpermute_b32 v188, v207, v186
	ds_bpermute_b32 v190, v207, v182
	ds_bpermute_b32 v189, v207, v187
	ds_bpermute_b32 v191, v207, v183
	ds_bpermute_b32 v192, v207, v184
	ds_bpermute_b32 v226, v207, v180
	ds_bpermute_b32 v193, v207, v185
	ds_bpermute_b32 v227, v207, v181
	s_waitcnt lgkmcnt(0)
	v_pk_mul_f32 v[176:177], v[176:177], v[192:193]
	v_pk_mul_f32 v[174:175], v[174:175], v[188:189]
	v_pk_fma_f32 v[184:185], v[184:185], v[168:169], v[176:177]
	v_pk_fma_f32 v[186:187], v[186:187], v[166:167], v[174:175]
	v_pk_mul_f32 v[166:167], v[172:173], v[226:227]
	v_pk_mul_f32 v[168:169], v[170:171], v[190:191]
	v_pk_fma_f32 v[180:181], v[180:181], v[156:157], v[166:167]
	v_pk_fma_f32 v[182:183], v[182:183], v[154:155], v[168:169]
.LBB0_237:
	v_ffbh_u32_e32 v157, v211
	v_min_u32_e32 v168, 32, v157
	v_lshlrev_b64 v[166:167], v168, v[210:211]
	v_min_u32_e32 v157, 1, v166
	v_or_b32_e32 v157, v167, v157
	v_cvt_f32_u32_e32 v166, v157
	v_cvt_pk_bf16_f32 v154, v186, v187
	v_cvt_pk_bf16_f32 v155, v184, v185
	v_cvt_pk_bf16_f32 v156, v182, v183
	v_cvt_pk_bf16_f32 v157, v180, v181
	global_store_dwordx4 v[178:179], v[154:157], off offset:256
	v_xor_b32_e32 v167, 0x80000000, v162
	v_xor_b32_e32 v169, 0x80000000, v164
	v_sub_u32_e32 v154, 32, v168
	v_ldexp_f32 v154, v166, v154
	v_fmamk_f32 v154, v154, 0x30800000, v240
	v_rsq_f32_e32 v166, v154
	v_xor_b32_e32 v154, 0x80000000, v158
	v_xor_b32_e32 v155, 0x80000000, v159
	v_xor_b32_e32 v156, 0x80000000, v160
	v_xor_b32_e32 v157, 0x80000000, v161
	v_xor_b32_e32 v168, 0x80000000, v163
	v_xor_b32_e32 v170, 0x80000000, v165
	v_cndmask_b32_e64 v161, v161, v157, s[6:7]
	v_cndmask_b32_e64 v160, v160, v156, s[6:7]
	v_cndmask_b32_e64 v159, v159, v155, s[6:7]
	v_cndmask_b32_e64 v158, v158, v154, s[6:7]
	v_cndmask_b32_e64 v157, v165, v170, s[6:7]
	v_cndmask_b32_e64 v156, v164, v169, s[6:7]
	v_cndmask_b32_e64 v155, v163, v168, s[6:7]
	v_cndmask_b32_e64 v154, v162, v167, s[6:7]
	v_pk_mul_f32 v[164:165], v[32:33], v[166:167] op_sel_hi:[1,0]
	v_pk_mul_f32 v[168:169], v[30:31], v[166:167] op_sel_hi:[1,0]
	v_pk_mul_f32 v[170:171], v[28:29], v[166:167] op_sel_hi:[1,0]
	s_and_b64 vcc, exec, s[4:5]
	v_pk_mul_f32 v[172:173], v[26:27], v[166:167] op_sel_hi:[1,0]
	s_cbranch_vccnz .LBB0_239
	v_xor_b32_e32 v167, 16, v238
	v_lshlrev_b32_e32 v167, 2, v167
	ds_bpermute_b32 v162, v167, v168
	ds_bpermute_b32 v174, v167, v172
	ds_bpermute_b32 v163, v167, v169
	ds_bpermute_b32 v175, v167, v173
	ds_bpermute_b32 v176, v167, v164
	ds_bpermute_b32 v178, v167, v170
	ds_bpermute_b32 v177, v167, v165
	ds_bpermute_b32 v179, v167, v171
	s_waitcnt lgkmcnt(0)
	v_pk_mul_f32 v[162:163], v[158:159], v[162:163]
	v_pk_mul_f32 v[176:177], v[160:161], v[176:177]
	v_pk_fma_f32 v[168:169], v[168:169], v[150:151], v[162:163]
	v_pk_mul_f32 v[162:163], v[156:157], v[178:179]
	v_pk_mul_f32 v[174:175], v[154:155], v[174:175]
	v_pk_fma_f32 v[164:165], v[164:165], v[152:153], v[176:177]
	v_pk_fma_f32 v[172:173], v[172:173], v[142:143], v[174:175]
	v_pk_fma_f32 v[170:171], v[170:171], v[144:145], v[162:163]
; #define GAS __attribute__((address_space(1)))
; __device__ __forceinline__ unsigned pk2(float lo, float hi) { f32x2_t v = {lo, hi}; bf16x2_t b = __builtin_convertvector(v, bf16x2_t); return __builtin_bit_cast(unsigned, b); }
; __device__ __forceinline__ void swap16(float& a, float& b) { asm volatile("s_nop 1\n\tv_permlane16_swap_b32 %0, %1\n\ts_nop 1" : "+v"(a), "+v"(b)); }
; __device__ __forceinline__ float rstd_of(u64 q) { return __builtin_amdgcn_rsqf((float)q * (1.0f / (1024.0f * SS_SCALE)) + EPS); }
;     __device__ __forceinline__ void operator()(const AccT& acc, const Unit& u, int, int, int, int) const {
;     ...
;                 for (int m = 0; m < 4; ++m) {
;                     const int row = row0 + ai * HALF + m * 16; const float rs = rstd_of(sq[ai][m]);
;                     bf16_t* rp = QK + (size_t)row * NQK + col0;
;                     f32x4 c0 = tc0[m], c1 = tc1[m], s0 = ts0[m], s1 = ts1[m];
;                     if (fq == 0) { s0 = -s0; s1 = -s1; }
; #pragma unroll
;                     for (int bj = 0; bj < 2; ++bj) {
;                         f32x4 v0 = acc[ai][bj][m][0] * rs, v1 = acc[ai][bj][m][1] * rs;
;                         if (ropew) {
;                             f32x4 p0, p1;
; #pragma unroll
;                             for (int e = 0; e < 4; ++e) { float a0 = v0[e], b0 = v0[e], a1 = v1[e], b1 = v1[e]; swap16(a0, b0); swap16(a1, b1);
;                                 p0[e] = (fq & 1) ? a0 : b0; p1[e] = (fq & 1) ? a1 : b1; }
;                             v0 = v0 * c0 + p0 * s0; v1 = v1 * c1 + p1 * s1;
;                         }
;                         u32x4 w; w.x = pk2(v0[0], v0[1]); w.y = pk2(v0[2], v0[3]); w.z = pk2(v1[0], v1[1]); w.w = pk2(v1[2], v1[3]);
;                         *(GAS u32x4*)(rp + bj * HALF) = w;
;                     }
.LBB0_239:
	v_add_u32_e32 v174, 0xa0, v206
	v_mov_b64_e32 v[162:163], s[10:11]
	v_mov_b32_e32 v167, v166
	v_mad_i64_i32 v[162:163], s[30:31], v174, s60, v[162:163]
	v_cvt_pk_bf16_f32 v175, v164, v165
	v_mov_b32_e32 v164, v166
	v_mov_b32_e32 v165, v166
	v_lshl_add_u64 v[162:163], v[224:225], 1, v[162:163]
	v_cvt_pk_bf16_f32 v174, v168, v169
	v_cvt_pk_bf16_f32 v176, v172, v173
	v_cvt_pk_bf16_f32 v177, v170, v171
	v_pk_mul_f32 v[168:169], v[24:25], v[164:165]
	v_pk_mul_f32 v[170:171], v[22:23], v[166:167]
	v_pk_mul_f32 v[164:165], v[20:21], v[164:165]
	s_and_b64 vcc, exec, s[4:5]
	v_pk_mul_f32 v[166:167], v[18:19], v[166:167]
	global_store_dwordx4 v[162:163], v[174:177], off
	s_cbranch_vccnz .LBB0_241
	v_xor_b32_e32 v180, 16, v238
	v_lshlrev_b32_e32 v180, 2, v180
	ds_bpermute_b32 v172, v180, v170
	ds_bpermute_b32 v174, v180, v166
	ds_bpermute_b32 v173, v180, v171
	ds_bpermute_b32 v175, v180, v167
	ds_bpermute_b32 v176, v180, v168
	ds_bpermute_b32 v178, v180, v164
	ds_bpermute_b32 v177, v180, v169
	ds_bpermute_b32 v179, v180, v165
	s_waitcnt lgkmcnt(0)
	v_pk_mul_f32 v[160:161], v[160:161], v[176:177]
	v_pk_mul_f32 v[158:159], v[158:159], v[172:173]
	v_pk_fma_f32 v[168:169], v[168:169], v[152:153], v[160:161]
	v_pk_fma_f32 v[170:171], v[170:171], v[150:151], v[158:159]
	v_pk_mul_f32 v[150:151], v[156:157], v[178:179]
	v_pk_mul_f32 v[152:153], v[154:155], v[174:175]
	v_pk_fma_f32 v[164:165], v[164:165], v[144:145], v[150:151]
	v_pk_fma_f32 v[166:167], v[166:167], v[142:143], v[152:153]
.LBB0_241:
	v_ffbh_u32_e32 v145, v209
	v_min_u32_e32 v152, 32, v145
	v_lshlrev_b64 v[150:151], v152, v[208:209]
	v_min_u32_e32 v145, 1, v150
	v_or_b32_e32 v145, v151, v145
	v_cvt_f32_u32_e32 v150, v145
	v_cvt_pk_bf16_f32 v142, v170, v171
	v_cvt_pk_bf16_f32 v143, v168, v169
	v_cvt_pk_bf16_f32 v144, v166, v167
	v_cvt_pk_bf16_f32 v145, v164, v165
	global_store_dwordx4 v[162:163], v[142:145], off offset:256
	v_xor_b32_e32 v153, 0x80000000, v146
	v_xor_b32_e32 v154, 0x80000000, v147
	v_sub_u32_e32 v142, 32, v152
	v_ldexp_f32 v142, v150, v142
	v_fmamk_f32 v142, v142, 0x30800000, v240
	v_rsq_f32_e32 v152, v142
	v_xor_b32_e32 v142, 0x80000000, v138
	v_xor_b32_e32 v143, 0x80000000, v139
	v_xor_b32_e32 v144, 0x80000000, v140
	v_xor_b32_e32 v145, 0x80000000, v141
	v_xor_b32_e32 v155, 0x80000000, v148
	v_xor_b32_e32 v156, 0x80000000, v149
	v_cndmask_b32_e64 v151, v141, v145, s[6:7]
	v_cndmask_b32_e64 v150, v140, v144, s[6:7]
	v_cndmask_b32_e64 v145, v139, v143, s[6:7]
	v_cndmask_b32_e64 v144, v138, v142, s[6:7]
	v_cndmask_b32_e64 v143, v149, v156, s[6:7]
	v_cndmask_b32_e64 v142, v148, v155, s[6:7]
	v_cndmask_b32_e64 v141, v147, v154, s[6:7]
	v_cndmask_b32_e64 v140, v146, v153, s[6:7]
	v_pk_mul_f32 v[146:147], v[16:17], v[152:153] op_sel_hi:[1,0]
	v_pk_mul_f32 v[148:149], v[14:15], v[152:153] op_sel_hi:[1,0]
	v_pk_mul_f32 v[154:155], v[12:13], v[152:153] op_sel_hi:[1,0]
	s_and_b64 vcc, exec, s[4:5]
	v_pk_mul_f32 v[156:157], v[10:11], v[152:153] op_sel_hi:[1,0]
	s_cbranch_vccnz .LBB0_243
	v_xor_b32_e32 v153, 16, v238
	v_lshlrev_b32_e32 v153, 2, v153
	ds_bpermute_b32 v138, v153, v148
	ds_bpermute_b32 v158, v153, v156
	ds_bpermute_b32 v139, v153, v149
	ds_bpermute_b32 v159, v153, v157
	ds_bpermute_b32 v160, v153, v146
	ds_bpermute_b32 v162, v153, v154
	ds_bpermute_b32 v161, v153, v147
	ds_bpermute_b32 v163, v153, v155
	s_waitcnt lgkmcnt(0)
	v_pk_mul_f32 v[138:139], v[144:145], v[138:139]
	v_pk_mul_f32 v[160:161], v[150:151], v[160:161]
	v_pk_fma_f32 v[148:149], v[148:149], v[134:135], v[138:139]
	v_pk_mul_f32 v[138:139], v[142:143], v[162:163]
	v_pk_mul_f32 v[158:159], v[140:141], v[158:159]
	v_pk_fma_f32 v[146:147], v[146:147], v[136:137], v[160:161]
	v_pk_fma_f32 v[156:157], v[156:157], v[130:131], v[158:159]
	v_pk_fma_f32 v[154:155], v[154:155], v[132:133], v[138:139]
.LBB0_243:
	v_add_u32_e32 v158, 0xb0, v206
	v_mov_b64_e32 v[138:139], s[10:11]
	v_mov_b32_e32 v153, v152
	v_mad_i64_i32 v[138:139], s[6:7], v158, s60, v[138:139]
	v_cvt_pk_bf16_f32 v159, v146, v147
	v_mov_b32_e32 v146, v152
	v_mov_b32_e32 v147, v152
	v_lshl_add_u64 v[138:139], v[224:225], 1, v[138:139]
	v_cvt_pk_bf16_f32 v158, v148, v149
	v_cvt_pk_bf16_f32 v160, v156, v157
	v_cvt_pk_bf16_f32 v161, v154, v155
	v_pk_mul_f32 v[148:149], v[8:9], v[146:147]
	v_pk_mul_f32 v[154:155], v[6:7], v[152:153]
	v_pk_mul_f32 v[146:147], v[4:5], v[146:147]
	s_and_b64 vcc, exec, s[4:5]
	v_pk_mul_f32 v[152:153], v[2:3], v[152:153]
	global_store_dwordx4 v[138:139], v[158:161], off
	s_cbranch_vccnz .LBB0_245
	v_xor_b32_e32 v164, 16, v238
	v_lshlrev_b32_e32 v164, 2, v164
	ds_bpermute_b32 v156, v164, v154
	ds_bpermute_b32 v158, v164, v152
	ds_bpermute_b32 v157, v164, v155
	ds_bpermute_b32 v159, v164, v153
	ds_bpermute_b32 v160, v164, v148
	ds_bpermute_b32 v162, v164, v146
	ds_bpermute_b32 v161, v164, v149
	ds_bpermute_b32 v163, v164, v147
	s_waitcnt lgkmcnt(0)
	v_pk_mul_f32 v[150:151], v[150:151], v[160:161]
	v_pk_mul_f32 v[144:145], v[144:145], v[156:157]
	v_pk_fma_f32 v[148:149], v[148:149], v[136:137], v[150:151]
	v_pk_fma_f32 v[154:155], v[154:155], v[134:135], v[144:145]
	v_pk_mul_f32 v[134:135], v[142:143], v[162:163]
	v_pk_mul_f32 v[136:137], v[140:141], v[158:159]
	v_pk_fma_f32 v[146:147], v[146:147], v[132:133], v[134:135]
	v_pk_fma_f32 v[152:153], v[152:153], v[130:131], v[136:137]
